# lever 7 (DPP instead of LDS round trips): mixer-B unit prologue - first four steps of the max|k_norm_g| wave reduction by v_max_f32_dpp instead of ds_bpermute
# speedup vs baseline: 1.0019x; 1.0019x over previous
; __device__ __forceinline__ unsigned cvtpk(float lo, float hi) { f32x2_t v = {lo, hi}; bf16x2_t b = __builtin_convertvector(v, bf16x2_t); return __builtin_bit_cast(unsigned, b); }
; __device__ __forceinline__ int tid_fresh() { int t = threadIdx.x; asm volatile("" : "+v"(t)); return t; }
; __device__ __forceinline__ float bflo(unsigned u) { return __uint_as_float(u << 16); }
; __device__ __forceinline__ float bfhi(unsigned u) { return __uint_as_float(u & 0xffff0000u); }
; #define WRITE_TILE(bufp) do { LAS unsigned char* _k = (bufp); LAS unsigned char* _v = (bufp) + 64 * KST; \
;         *(LAS u32x4*)(_k + key * KST + ch * 16) = kreg; \
;         *(LAS u32x4*)(_v + key * VST + ch * 16) = vreg; } while (0)
; __device__ __forceinline__ void attnB_unit(LAS unsigned char* lds, const Args& A, int unit, const float* kng, bool do_store = true) {
;     const int tid = tid_fresh(), wave = tid >> 6, lane = tid & 63, ql = lane & 31, hh = lane >> 5;
;     const int qblk = unit & 31, hq = (unit >> 5) & 7, b = unit >> 8, kvh = hq >> 2;
;     const bf16* Qp = (const bf16*)(A.ws + WS_QB) + ((size_t)((b * 8 + hq) * 8192 + qblk * 256 + wave * 32 + ql) * 64);
;     bf16x8 qf[4];
; #pragma unroll
;     for (int s = 0; s < 4; ++s) { const u32x4 qw = *(const u32x4*)(Qp + 16 * s + 8 * hh);
;         u32x4 qs; qs.x = cvtpk(bflo(qw.x) * QK_C, bfhi(qw.x) * QK_C); qs.y = cvtpk(bflo(qw.y) * QK_C, bfhi(qw.y) * QK_C); qs.z = cvtpk(bflo(qw.z) * QK_C, bfhi(qw.z) * QK_C); qs.w = cvtpk(bflo(qw.w) * QK_C, bfhi(qw.w) * QK_C);
;         qf[s] = __builtin_bit_cast(bf16x8, qs); }
;     const int key = tid >> 3, ch = tid & 7;
;     const bf16* Kg = (const bf16*)(A.ws + WS_KB) + ((size_t)((b * 2 + kvh) * 8192 + key) * 64 + ch * 8);
;     const bf16* Vg = (const bf16*)(A.ws + WS_VB) + ((size_t)((b * 2 + kvh) * 8192 + key) * 64 + ch * 8);
;     f32x16 o0, o1;
; #pragma unroll
;     for (int i = 0; i < 16; ++i) { o0[i] = 0.f; o1[i] = 0.f; }
;     float m_used = -1e30f, l = 0.f; float lp[4] = {0.f, 0.f, 0.f, 0.f};
;     u32x4 kreg = *(const u32x4*)Kg, vreg = *(const u32x4*)Vg;
;     u32x4 kq1 = *(const u32x4*)(Kg + (size_t)64 * 64), vq1 = *(const u32x4*)(Vg + (size_t)64 * 64), kq0 = *(const u32x4*)(Kg + (size_t)2 * 64 * 64), vq0 = *(const u32x4*)(Vg + (size_t)2 * 64 * 64);
;     ...
;     __syncthreads();
;     WRITE_TILE(lds);
;     kreg = kq1; vreg = vq1;
;     WRITE_TILE(lds + BUF_B);
;     __syncthreads();
.LBB0_314:
	s_bfe_u32 s8, s4, 0x30005
	s_ashr_i32 s9, s4, 8
	s_lshl_b32 s5, s9, 16
	s_lshl_b32 s6, s8, 13
	s_lshl_b32 s7, s4, 8
	v_mov_b32_e32 v32, v212
	s_and_b32 s10, s7, 0x1f00
	s_or_b32 s5, s5, s6
	s_or_b32 s5, s5, s10
	v_and_b32_e32 v210, 31, v32
	v_ashrrev_i32_e32 v0, 1, v32
	v_and_b32_e32 v211, 0xffffffe0, v0
	v_or_b32_e32 v0, s5, v210
	v_add_u32_e32 v0, v0, v211
	v_ashrrev_i32_e32 v1, 31, v0
	v_readlane_b32 s6, v254, 51
	v_bfe_u32 v33, v32, 5, 1
	v_lshlrev_b64 v[0:1], 7, v[0:1]
	v_readlane_b32 s7, v254, 52
	v_lshlrev_b32_e32 v184, 4, v33
	s_lshl_b32 s4, s4, 6
	v_lshl_add_u64 v[0:1], s[6:7], 0, v[0:1]
	v_lshl_add_u64 v[4:5], v[0:1], 0, v[184:185]
	global_load_dwordx4 v[20:23], v[4:5], off
	global_load_dwordx4 v[24:27], v[4:5], off offset:32
	global_load_dwordx4 v[28:31], v[4:5], off offset:64
	global_load_dwordx4 v[36:39], v[4:5], off offset:96
	s_lshl_b32 s5, s9, 14
	s_and_b32 s4, s4, 0x2000
	v_ashrrev_i32_e32 v34, 3, v32
	s_or_b32 s4, s4, s5
	v_mul_lo_u32 v224, v34, s88
	v_mul_u32_u24_e32 v225, 0x90, v210
	v_add3_u32 v44, 0, v225, v184
	v_and_b32_e32 v35, 63, v32
	v_lshlrev_b32_e32 v35, 2, v35
	v_mov_b32_e32 v172, 0
	v_readlane_b32 s6, v255, 48
	v_readlane_b32 s7, v255, 49
	v_lshlrev_b32_e32 v2, 4, v32
	v_and_b32_e32 v223, 0x70, v2
	v_add_u32_e32 v0, s4, v34
	v_ashrrev_i32_e32 v1, 31, v0
	v_lshlrev_b64 v[0:1], 7, v[0:1]
	v_readlane_b32 s4, v254, 53
	v_or_b32_e32 v0, v0, v223
	v_readlane_b32 s5, v254, 54
	global_load_dword v35, v35, s[6:7]
	s_nop 1
	v_lshl_add_u64 v[168:169], s[4:5], 0, v[0:1]
	v_readlane_b32 s4, v254, 8
	v_readlane_b32 s5, v254, 9
	s_nop 1
	v_lshl_add_u64 v[170:171], s[4:5], 0, v[0:1]
	s_movk_i32 s4, 0x2000
	v_add_co_u32_e32 v8, vcc, s4, v168
	global_load_dwordx4 v[0:3], v[168:169], off
	global_load_dwordx4 v[4:7], v[170:171], off
	v_addc_co_u32_e32 v9, vcc, 0, v169, vcc
	v_add_co_u32_e32 v12, vcc, s4, v170
	global_load_dwordx4 v[8:11], v[8:9], off
	s_nop 0
	v_addc_co_u32_e32 v13, vcc, 0, v171, vcc
	global_load_dwordx4 v[12:15], v[12:13], off
	s_movk_i32 s4, 0x4000
	v_add_co_u32_e32 v16, vcc, s4, v168
	s_nop 1
	v_addc_co_u32_e32 v17, vcc, 0, v169, vcc
	global_load_dwordx4 v[144:147], v[16:17], off
	v_add_co_u32_e32 v16, vcc, s4, v170
	s_movk_i32 s4, 0xffd0
	s_nop 0
	v_addc_co_u32_e32 v17, vcc, 0, v171, vcc
	global_load_dwordx4 v[148:151], v[16:17], off
	s_waitcnt vmcnt(6)
	v_lshlrev_b32_e32 v40, 16, v20
	v_and_b32_e32 v41, 0xffff0000, v20
	v_pk_mul_f32 v[40:41], v[40:41], s[92:93] op_sel_hi:[1,0]
	v_cvt_pk_bf16_f32 v128, v40, v41
	v_lshlrev_b32_e32 v42, 16, v21
	v_and_b32_e32 v43, 0xffff0000, v21
	v_pk_mul_f32 v[42:43], v[42:43], s[92:93] op_sel_hi:[1,0]
	v_cvt_pk_bf16_f32 v129, v42, v43
	v_lshlrev_b32_e32 v40, 16, v22
	v_and_b32_e32 v41, 0xffff0000, v22
	v_pk_mul_f32 v[40:41], v[40:41], s[92:93] op_sel_hi:[1,0]
	v_cvt_pk_bf16_f32 v130, v40, v41
	v_lshlrev_b32_e32 v42, 16, v23
	v_and_b32_e32 v43, 0xffff0000, v23
	v_pk_mul_f32 v[42:43], v[42:43], s[92:93] op_sel_hi:[1,0]
	v_cvt_pk_bf16_f32 v131, v42, v43
	v_lshlrev_b32_e32 v40, 16, v24
	v_and_b32_e32 v41, 0xffff0000, v24
	v_pk_mul_f32 v[40:41], v[40:41], s[92:93] op_sel_hi:[1,0]
	v_cvt_pk_bf16_f32 v132, v40, v41
	v_lshlrev_b32_e32 v42, 16, v25
	v_and_b32_e32 v43, 0xffff0000, v25
	v_pk_mul_f32 v[42:43], v[42:43], s[92:93] op_sel_hi:[1,0]
	v_cvt_pk_bf16_f32 v133, v42, v43
	v_lshlrev_b32_e32 v40, 16, v26
	v_and_b32_e32 v41, 0xffff0000, v26
	v_pk_mul_f32 v[40:41], v[40:41], s[92:93] op_sel_hi:[1,0]
	v_cvt_pk_bf16_f32 v134, v40, v41
	v_lshlrev_b32_e32 v42, 16, v27
	v_and_b32_e32 v43, 0xffff0000, v27
	v_pk_mul_f32 v[42:43], v[42:43], s[92:93] op_sel_hi:[1,0]
	v_cvt_pk_bf16_f32 v135, v42, v43
	v_lshlrev_b32_e32 v40, 16, v28
	v_and_b32_e32 v41, 0xffff0000, v28
	v_pk_mul_f32 v[40:41], v[40:41], s[92:93] op_sel_hi:[1,0]
	v_cvt_pk_bf16_f32 v136, v40, v41
	v_lshlrev_b32_e32 v42, 16, v29
	v_and_b32_e32 v43, 0xffff0000, v29
	v_pk_mul_f32 v[42:43], v[42:43], s[92:93] op_sel_hi:[1,0]
	v_cvt_pk_bf16_f32 v137, v42, v43
	v_lshlrev_b32_e32 v40, 16, v30
	v_and_b32_e32 v41, 0xffff0000, v30
	v_pk_mul_f32 v[40:41], v[40:41], s[92:93] op_sel_hi:[1,0]
	v_cvt_pk_bf16_f32 v138, v40, v41
	v_lshlrev_b32_e32 v42, 16, v31
	v_and_b32_e32 v43, 0xffff0000, v31
	v_pk_mul_f32 v[42:43], v[42:43], s[92:93] op_sel_hi:[1,0]
	v_cvt_pk_bf16_f32 v139, v42, v43
	v_lshlrev_b32_e32 v40, 16, v36
	v_and_b32_e32 v41, 0xffff0000, v36
	v_pk_mul_f32 v[40:41], v[40:41], s[92:93] op_sel_hi:[1,0]
	v_cvt_pk_bf16_f32 v140, v40, v41
	v_lshlrev_b32_e32 v42, 16, v37
	v_and_b32_e32 v43, 0xffff0000, v37
	v_pk_mul_f32 v[42:43], v[42:43], s[92:93] op_sel_hi:[1,0]
	v_cvt_pk_bf16_f32 v141, v42, v43
	v_lshlrev_b32_e32 v40, 16, v38
	v_and_b32_e32 v41, 0xffff0000, v38
	v_pk_mul_f32 v[40:41], v[40:41], s[92:93] op_sel_hi:[1,0]
	v_cvt_pk_bf16_f32 v142, v40, v41
	v_lshlrev_b32_e32 v42, 16, v39
	v_and_b32_e32 v43, 0xffff0000, v39
	v_pk_mul_f32 v[42:43], v[42:43], s[92:93] op_sel_hi:[1,0]
	v_cvt_pk_bf16_f32 v143, v42, v43
	v_and_b32_e32 v45, 0xffff0000, v140
	v_add3_u32 v16, 0, v224, v223
	s_barrier
	s_waitcnt vmcnt(5)
	ds_write_b128 v16, v[0:3]
	v_mul_lo_u32 v2, v34, 48
	v_add_u32_e32 v0, v16, v2
	s_waitcnt vmcnt(4)
	ds_write_b128 v0, v[4:7] offset:9216
	v_mad_u64_u32 v[0:1], s[4:5], v34, s4, v[0:1]
	s_waitcnt vmcnt(3)
	ds_write_b128 v0, v[8:11] offset:21504
	v_add_u32_e32 v0, v0, v2
	v_readlane_b32 s4, v255, 48
	s_waitcnt vmcnt(2)
	ds_write_b128 v0, v[12:15] offset:30720
	s_waitcnt lgkmcnt(0)
	s_barrier
; __device__ __forceinline__ float bflo(unsigned u) { return __uint_as_float(u << 16); }
; __device__ __forceinline__ float bfhi(unsigned u) { return __uint_as_float(u & 0xffff0000u); }
; #define QK_TILE(kbp, d0, d1) do { _Pragma("unroll") for (int s = 0; s < 4; ++s) { \
;         const bf16x8 _k0 = *(const LAS bf16x8*)((kbp) + ql * KST + hh * 16 + 32 * s), _k1 = *(const LAS bf16x8*)((kbp) + (32 + ql) * KST + hh * 16 + 32 * s); \
;         d0 = MFMA32(_k0, qf[s], d0); d1 = MFMA32(_k1, qf[s], d1); } } while (0)
; __device__ __forceinline__ void attnB_unit(LAS unsigned char* lds, const Args& A, int unit, const float* kng, bool do_store = true) {
;     ...
;     QK_TILE(lds, c0, c1);
;     float mx = fmaxf(c0[0], c1[0]);
; #pragma unroll
;     for (int i = 1; i < 16; ++i) mx = fmaxf(mx, fmaxf(c0[i], c1[i]));
;     mx = fmaxf(mx, __shfl_xor(mx, 32));
;     float qn2 = 0.f;
; #pragma unroll
;     for (int s = 0; s < 4; ++s) { const u32x4 qw = __builtin_bit_cast(u32x4, qf[s]);
;         qn2 += bflo(qw.x) * bflo(qw.x) + bfhi(qw.x) * bfhi(qw.x) + bflo(qw.y) * bflo(qw.y) + bfhi(qw.y) * bfhi(qw.y) + bflo(qw.z) * bflo(qw.z) + bfhi(qw.z) * bfhi(qw.z) + bflo(qw.w) * bflo(qw.w) + bfhi(qw.w) * bfhi(qw.w); }
;     qn2 += __shfl_xor(qn2, 32);
;     float gk = fabsf(kng[lane]);
; #pragma unroll
;     for (int o = 1; o < 64; o <<= 1) gk = fmaxf(gk, __shfl_xor(gk, o));
;     const bool fast = __all(sqrtf(qn2) * 8.0f * gk * 1.05f <= 48.0f) != 0;
	ds_read_b128 v[0:3], v44 offset:4608
	ds_read_b128 v[4:7], v44
	ds_read_b128 v[36:39], v44 offset:32
	ds_read_b128 v[40:43], v44 offset:4640
	s_waitcnt lgkmcnt(2)
	v_mfma_f32_32x32x16_bf16 v[16:31], v[4:7], v[128:131], 0
	v_readlane_b32 s5, v255, 49
	v_mfma_f32_32x32x16_bf16 v[0:15], v[0:3], v[128:131], 0
	s_waitcnt lgkmcnt(1)
	v_mfma_f32_32x32x16_bf16 v[16:31], v[36:39], v[132:135], v[16:31]
	s_waitcnt lgkmcnt(0)
	v_mfma_f32_32x32x16_bf16 v[0:15], v[40:43], v[132:135], v[0:15]
	ds_read_b128 v[36:39], v44 offset:64
	ds_read_b128 v[40:43], v44 offset:4672
	s_waitcnt lgkmcnt(1)
	v_mfma_f32_32x32x16_bf16 v[16:31], v[36:39], v[136:139], v[16:31]
	s_waitcnt lgkmcnt(0)
	v_mfma_f32_32x32x16_bf16 v[0:15], v[40:43], v[136:139], v[0:15]
	ds_read_b128 v[36:39], v44 offset:96
	ds_read_b128 v[40:43], v44 offset:4704
	v_and_b32_e32 v44, 0xffff0000, v136
	v_mul_f32_e64 v44, v44, v44
	v_mul_f32_e64 v45, v45, v45
	s_mov_b32 s4, 0xf800000
	s_waitcnt lgkmcnt(1)
	v_mfma_f32_32x32x16_bf16 v[16:31], v[36:39], v[140:143], v[16:31]
	s_waitcnt lgkmcnt(0)
	v_mfma_f32_32x32x16_bf16 v[0:15], v[40:43], v[140:143], v[0:15]
	s_nop 9
	v_max_f32_e32 v37, v17, v17
	v_max_f32_e32 v38, v18, v18
	v_max_f32_e32 v39, v19, v19
	v_and_b32_e32 v43, 0xffff0000, v132
	v_and_b32_e32 v42, 0xffff0000, v128
	v_lshlrev_b32_e32 v41, 16, v132
	v_lshlrev_b32_e32 v40, 16, v128
	v_max_f32_e32 v36, v1, v1
	v_max_f32_e32 v36, v37, v36
	v_max_f32_e32 v37, v2, v2
	v_max_f32_e32 v37, v38, v37
	v_max_f32_e32 v38, v3, v3
	v_max3_f32 v36, v16, v0, v36
	v_max_f32_e32 v38, v39, v38
	v_max3_f32 v36, v36, v37, v38
	v_max_f32_e32 v37, v4, v4
	v_max_f32_e32 v38, v20, v20
	v_max_f32_e32 v37, v38, v37
	v_max_f32_e32 v38, v5, v5
	v_max_f32_e32 v39, v21, v21
	v_max_f32_e32 v38, v39, v38
	v_max3_f32 v36, v36, v37, v38
	v_max_f32_e32 v37, v6, v6
	v_max_f32_e32 v38, v22, v22
	v_max_f32_e32 v37, v38, v37
	v_max_f32_e32 v38, v7, v7
	v_max_f32_e32 v39, v23, v23
	v_max_f32_e32 v38, v39, v38
	v_pk_mul_f32 v[42:43], v[42:43], v[42:43]
	v_max3_f32 v36, v36, v37, v38
	v_max_f32_e32 v37, v8, v8
	v_max_f32_e32 v38, v24, v24
	v_pk_fma_f32 v[40:41], v[40:41], v[40:41], v[42:43]
	v_lshlrev_b32_e32 v42, 16, v129
	v_lshlrev_b32_e32 v43, 16, v133
	v_max_f32_e32 v37, v38, v37
	v_max_f32_e32 v38, v9, v9
	v_max_f32_e32 v39, v25, v25
	v_pk_fma_f32 v[40:41], v[42:43], v[42:43], v[40:41]
	v_and_b32_e32 v43, 0xffff0000, v133
	v_and_b32_e32 v42, 0xffff0000, v129
	v_max_f32_e32 v38, v39, v38
	v_pk_fma_f32 v[40:41], v[42:43], v[42:43], v[40:41]
	v_lshlrev_b32_e32 v43, 16, v134
	v_lshlrev_b32_e32 v42, 16, v130
	v_max3_f32 v36, v36, v37, v38
	v_max_f32_e32 v37, v10, v10
	v_max_f32_e32 v38, v26, v26
	v_pk_fma_f32 v[40:41], v[42:43], v[42:43], v[40:41]
	v_and_b32_e32 v43, 0xffff0000, v134
	v_and_b32_e32 v42, 0xffff0000, v130
	v_max_f32_e32 v37, v38, v37
	v_max_f32_e32 v38, v11, v11
	v_max_f32_e32 v39, v27, v27
	v_pk_fma_f32 v[40:41], v[42:43], v[42:43], v[40:41]
	v_lshlrev_b32_e32 v43, 16, v135
	v_lshlrev_b32_e32 v42, 16, v131
	v_max_f32_e32 v38, v39, v38
	v_pk_fma_f32 v[40:41], v[42:43], v[42:43], v[40:41]
	v_and_b32_e32 v43, 0xffff0000, v135
	v_and_b32_e32 v42, 0xffff0000, v131
	v_max3_f32 v36, v36, v37, v38
	v_max_f32_e32 v37, v12, v12
	v_max_f32_e32 v38, v28, v28
	v_pk_fma_f32 v[40:41], v[42:43], v[42:43], v[40:41]
	v_lshlrev_b32_e32 v43, 16, v140
	v_lshlrev_b32_e32 v42, 16, v136
	v_max_f32_e32 v37, v38, v37
	v_max_f32_e32 v38, v13, v13
	v_max_f32_e32 v39, v29, v29
	v_pk_fma_f32 v[42:43], v[42:43], v[42:43], v[44:45]
	v_lshlrev_b32_e32 v44, 16, v137
	v_lshlrev_b32_e32 v45, 16, v141
	v_max_f32_e32 v38, v39, v38
	v_pk_fma_f32 v[42:43], v[44:45], v[44:45], v[42:43]
	v_and_b32_e32 v45, 0xffff0000, v141
	v_and_b32_e32 v44, 0xffff0000, v137
	v_max3_f32 v36, v36, v37, v38
	v_max_f32_e32 v37, v14, v14
	v_max_f32_e32 v38, v30, v30
	v_pk_fma_f32 v[42:43], v[44:45], v[44:45], v[42:43]
	v_lshlrev_b32_e32 v45, 16, v142
	v_lshlrev_b32_e32 v44, 16, v138
	v_max_f32_e32 v37, v38, v37
	v_max_f32_e32 v38, v15, v15
	v_max_f32_e32 v39, v31, v31
	v_pk_fma_f32 v[42:43], v[44:45], v[44:45], v[42:43]
	v_and_b32_e32 v45, 0xffff0000, v142
	v_and_b32_e32 v44, 0xffff0000, v138
	v_max_f32_e32 v38, v39, v38
	v_pk_fma_f32 v[42:43], v[44:45], v[44:45], v[42:43]
	v_lshlrev_b32_e32 v45, 16, v143
	v_lshlrev_b32_e32 v44, 16, v139
	v_max3_f32 v36, v36, v37, v38
	v_and_b32_e32 v38, 64, v217
	v_pk_fma_f32 v[42:43], v[44:45], v[44:45], v[42:43]
	v_and_b32_e32 v45, 0xffff0000, v143
	v_and_b32_e32 v44, 0xffff0000, v139
	v_xor_b32_e32 v37, 32, v217
	v_add_u32_e32 v38, 64, v38
	v_pk_fma_f32 v[42:43], v[44:45], v[44:45], v[42:43]
	v_add_f32_e32 v39, v40, v41
	v_cmp_lt_i32_e32 vcc, v37, v38
	v_add_f32_e32 v39, v39, v42
	v_xor_b32_e32 v42, 1, v217
	v_cndmask_b32_e32 v37, v217, v37, vcc
	v_cmp_lt_i32_e32 vcc, v42, v38
	s_waitcnt vmcnt(0)
	v_and_b32_e32 v41, 0x7fffffff, v35
	v_max_f32_e64 v35, |v35|, |v35|
	v_cndmask_b32_e32 v42, v217, v42, vcc
	v_lshlrev_b32_e32 v42, 2, v42
	v_lshlrev_b32_e32 v226, 2, v37
	v_add_f32_e32 v39, v39, v43
	ds_bpermute_b32 v40, v226, v39
	ds_bpermute_b32 v37, v226, v36
	s_nop 1
	v_max_f32_dpp v35, v35, v35 quad_perm:[1,0,3,2] row_mask:0xf bank_mask:0xf
	s_nop 1
	v_max_f32_dpp v35, v35, v35 quad_perm:[2,3,0,1] row_mask:0xf bank_mask:0xf
	s_nop 1
	v_max_f32_dpp v35, v35, v35 row_half_mirror row_mask:0xf bank_mask:0xf
	s_nop 1
	v_max_f32_dpp v35, v35, v35 row_mirror row_mask:0xf bank_mask:0xf
	s_nop 1
	v_xor_b32_e32 v41, 16, v217
	v_cmp_lt_i32_e32 vcc, v41, v38
	s_nop 1
	v_cndmask_b32_e32 v38, v217, v41, vcc
	v_lshlrev_b32_e32 v38, 2, v38
	ds_bpermute_b32 v38, v38, v35
	s_waitcnt lgkmcnt(0)
	v_max_f32_e32 v38, v38, v38
	v_max_f32_e32 v35, v35, v38
	ds_bpermute_b32 v38, v226, v35
	s_waitcnt lgkmcnt(0)
	v_max_f32_e32 v38, v38, v38
	v_max_f32_e32 v35, v35, v38
	v_add_f32_e32 v38, v39, v40
	v_cmp_gt_f32_e32 vcc, s4, v38
	v_mul_f32_e32 v39, 0x4f800000, v38
	s_nop 0
	v_cndmask_b32_e32 v38, v38, v39, vcc
	v_sqrt_f32_e32 v39, v38
	s_nop 0
	v_add_u32_e32 v40, -1, v39
	v_fma_f32 v41, -v40, v39, v38
	v_cmp_ge_f32_e64 s[4:5], 0, v41
	v_add_u32_e32 v41, 1, v39
	s_nop 0
	v_cndmask_b32_e64 v40, v39, v40, s[4:5]
	v_fma_f32 v39, -v41, v39, v38
	v_cmp_lt_f32_e64 s[4:5], 0, v39
	s_nop 1
	v_cndmask_b32_e64 v39, v40, v41, s[4:5]
	v_mul_f32_e32 v40, 0x37800000, v39
	v_cndmask_b32_e32 v39, v39, v40, vcc
	v_cmp_class_f32_e32 vcc, v38, v216
	s_mov_b32 s4, 0x42400000
	s_nop 0
	v_cndmask_b32_e32 v38, v39, v38, vcc
	v_mul_f32_e32 v38, 0x41000000, v38
	v_mul_f32_e32 v35, v38, v35
	v_mul_f32_e32 v35, 0x3f866666, v35
	v_cmp_ge_f32_e32 vcc, s4, v35
	s_cmp_lg_u64 vcc, exec
	s_cselect_b64 s[4:5], -1, 0
	s_cmp_eq_u64 vcc, exec
	s_cbranch_scc1 .LBB0_316
; __device__ __forceinline__ void attnB_unit(LAS unsigned char* lds, const Args& A, int unit, const float* kng, bool do_store = true) {
;     ...
;     else {
;         m_used = mx;
; #pragma unroll
;         for (int i = 0; i < 16; ++i) { c0[i] -= m_used; c1[i] -= m_used; }
;         mx = 0.f;
	v_max_f32_e32 v35, v37, v37
	v_max_f32_e32 v36, v36, v36
	v_max_f32_e32 v172, v36, v35
	v_sub_f32_e32 v31, v31, v172
	v_sub_f32_e32 v30, v30, v172
	v_sub_f32_e32 v29, v29, v172
	v_sub_f32_e32 v28, v28, v172
	v_sub_f32_e32 v27, v27, v172
	v_sub_f32_e32 v26, v26, v172
	v_sub_f32_e32 v25, v25, v172
	v_sub_f32_e32 v24, v24, v172
	v_sub_f32_e32 v23, v23, v172
	v_sub_f32_e32 v22, v22, v172
	v_sub_f32_e32 v21, v21, v172
	v_sub_f32_e32 v20, v20, v172
	v_sub_f32_e32 v19, v19, v172
	v_sub_f32_e32 v18, v18, v172
	v_sub_f32_e32 v17, v17, v172
	v_sub_f32_e32 v16, v16, v172
	v_sub_f32_e32 v15, v15, v172
	v_sub_f32_e32 v14, v14, v172
	v_sub_f32_e32 v13, v13, v172
	v_sub_f32_e32 v12, v12, v172
	v_sub_f32_e32 v11, v11, v172
	v_sub_f32_e32 v10, v10, v172
	v_sub_f32_e32 v9, v9, v172
	v_sub_f32_e32 v8, v8, v172
	v_sub_f32_e32 v7, v7, v172
	v_sub_f32_e32 v6, v6, v172
	v_sub_f32_e32 v5, v5, v172
	v_sub_f32_e32 v4, v4, v172
	v_sub_f32_e32 v3, v3, v172
	v_sub_f32_e32 v2, v2, v172
	v_sub_f32_e32 v1, v1, v172
	v_sub_f32_e32 v0, v0, v172
